# last-layer FFN-down: sample-row units split-K 16 ways (schedule of the other layers) + fold of the partial slabs after the final grid barrier; scan stage-2 LDS reads batched
# speedup vs baseline: 1.0079x; 1.0079x over previous
.LBB0_538:
	s_waitcnt lgkmcnt(0)
	s_barrier
	ds_read2st64_b32 v[176:177], v106 offset0:244 offset1:245
	ds_read2st64_b32 v[178:179], v106 offset0:246 offset1:247
	ds_read2st64_b32 v[180:181], v106 offset0:248 offset1:249
	ds_read2st64_b32 v[182:183], v106 offset0:250 offset1:251
	ds_read2st64_b32 v[184:185], v106 offset0:252 offset1:253
	ds_read2st64_b32 v[186:187], v106 offset0:254 offset1:255
	ds_read2st64_b32 v[188:189], v107 offset0:12 offset1:13
	ds_read2st64_b32 v[190:191], v107 offset0:14 offset1:15
	ds_read2st64_b32 v[192:193], v107 offset0:16 offset1:17
	ds_read2st64_b32 v[194:195], v107 offset0:18 offset1:19
	ds_read2st64_b32 v[196:197], v107 offset0:20 offset1:21
	ds_read2st64_b32 v[198:199], v107 offset0:22 offset1:23
	v_readlane_b32 s8, v250, 6
	v_readlane_b32 s9, v250, 7
	s_andn2_b64 vcc, exec, s[24:25]
	s_waitcnt lgkmcnt(11)
	ds_read2st64_b32 v[200:201], v107 offset0:24 offset1:25
	v_add_f32_e32 v3, 0, v176
	v_add_f32_e32 v3, v3, v177
	s_waitcnt lgkmcnt(11)
	ds_read2st64_b32 v[202:203], v107 offset0:26 offset1:27
	v_add_f32_e32 v3, v3, v178
	v_add_f32_e32 v3, v3, v179
	v_cndmask_b32_e64 v42, 0, v3, s[8:9]
	v_readlane_b32 s8, v250, 4
	v_readlane_b32 s9, v250, 5
	s_waitcnt lgkmcnt(11)
	ds_read2st64_b32 v[204:205], v107 offset0:28 offset1:29
	v_add_f32_e32 v3, v3, v180
	v_add_f32_e32 v3, v3, v181
	s_waitcnt lgkmcnt(11)
	ds_read2st64_b32 v[206:207], v107 offset0:30 offset1:31
	v_add_f32_e32 v3, v3, v182
	v_add_f32_e32 v3, v3, v183
	v_cndmask_b32_e64 v42, v42, v3, s[8:9]
	v_readlane_b32 s8, v250, 24
	v_readlane_b32 s9, v250, 25
	s_waitcnt lgkmcnt(11)
	v_add_f32_e32 v3, v3, v184
	v_add_f32_e32 v3, v3, v185
	s_waitcnt lgkmcnt(10)
	v_add_f32_e32 v3, v3, v186
	v_add_f32_e32 v3, v3, v187
	v_cndmask_b32_e64 v42, v42, v3, s[2:3]
	s_waitcnt lgkmcnt(9)
	v_add_f32_e32 v3, v3, v188
	v_add_f32_e32 v3, v3, v189
	s_waitcnt lgkmcnt(8)
	v_add_f32_e32 v3, v3, v190
	v_add_f32_e32 v3, v3, v191
	v_cndmask_b32_e64 v42, v42, v3, s[78:79]
	s_waitcnt lgkmcnt(7)
	v_add_f32_e32 v3, v3, v192
	v_add_f32_e32 v3, v3, v193
	s_waitcnt lgkmcnt(6)
	v_add_f32_e32 v3, v3, v194
	v_add_f32_e32 v3, v3, v195
	v_cndmask_b32_e64 v42, v42, v3, s[52:53]
	s_waitcnt lgkmcnt(5)
	v_add_f32_e32 v3, v3, v196
	v_add_f32_e32 v3, v3, v197
	s_waitcnt lgkmcnt(4)
	v_add_f32_e32 v3, v3, v198
	v_add_f32_e32 v3, v3, v199
	v_cndmask_b32_e64 v42, v42, v3, s[54:55]
	s_waitcnt lgkmcnt(3)
	v_add_f32_e32 v3, v3, v200
	v_add_f32_e32 v3, v3, v201
	s_waitcnt lgkmcnt(2)
	v_add_f32_e32 v3, v3, v202
	v_add_f32_e32 v3, v3, v203
	v_cndmask_b32_e64 v42, v42, v3, s[8:9]
	s_waitcnt lgkmcnt(1)
	v_add_f32_e32 v3, v3, v204
	v_add_f32_e32 v3, v3, v205
	s_waitcnt lgkmcnt(0)
	v_add_f32_e32 v3, v3, v206
	v_add_f32_e32 v4, v22, v42
	v_mul_f32_e32 v22, 0xbfb8aa3b, v42
	v_exp_f32_e32 v22, v22
	v_add_f32_e32 v3, v3, v207
	v_mul_f32_e32 v5, 0xbfb8aa3b, v4
	v_exp_f32_e32 v5, v5
	v_mul_f32_e32 v42, 0x3fb8aa3b, v4
	v_exp_f32_e32 v42, v42
	v_mul_f32_e32 v22, v32, v22
	v_cvt_pk_bf16_f32 v22, v22, v2
	v_add_u32_e32 v32, s33, v108
	v_sub_f32_e32 v43, v4, v3
	ds_write_b16 v32, v22
	v_mul_f32_e32 v22, v30, v5
	v_mul_f32_e32 v43, 0x3fb8aa3b, v43
	v_cvt_pk_bf16_f32 v22, v22, v2
	v_exp_f32_e32 v43, v43
	ds_write_b16 v32, v22 offset:4608
	v_mul_f32_e32 v22, v23, v42
	v_cvt_pk_bf16_f32 v22, v22, v2
	ds_write_b16 v32, v22 offset:9216
	v_mul_f32_e32 v22, v31, v42
	v_cvt_pk_bf16_f32 v22, v22, v2
	ds_write_b16 v32, v22 offset:13824
	v_mul_f32_e32 v22, v23, v43
	v_cvt_pk_bf16_f32 v22, v22, v2
	ds_write_b16 v32, v22 offset:18432
	v_mul_f32_e32 v22, v31, v43
	v_cvt_pk_bf16_f32 v22, v22, v2
	v_add_f32_e32 v4, v24, v4
	ds_write_b16 v32, v22 offset:23040
	v_mul_f32_e32 v22, 0xbfb8aa3b, v4
	v_exp_f32_e32 v22, v22
	v_mul_f32_e32 v23, 0x3fb8aa3b, v4
	v_exp_f32_e32 v23, v23
	v_mul_f32_e32 v5, v35, v5
	v_cvt_pk_bf16_f32 v5, v5, v2
	v_add_u32_e32 v30, s91, v108
	v_sub_f32_e32 v24, v4, v3
	ds_write_b16 v30, v5
	v_mul_f32_e32 v5, v33, v22
	v_mul_f32_e32 v24, 0x3fb8aa3b, v24
	v_cvt_pk_bf16_f32 v5, v5, v2
	v_exp_f32_e32 v24, v24
	ds_write_b16 v30, v5 offset:4608
	v_mul_f32_e32 v5, v25, v23
	v_cvt_pk_bf16_f32 v5, v5, v2
	ds_write_b16 v30, v5 offset:9216
	v_mul_f32_e32 v5, v34, v23
	v_cvt_pk_bf16_f32 v5, v5, v2
	ds_write_b16 v30, v5 offset:13824
	v_mul_f32_e32 v5, v25, v24
	v_cvt_pk_bf16_f32 v5, v5, v2
	ds_write_b16 v30, v5 offset:18432
	v_mul_f32_e32 v5, v34, v24
	v_cvt_pk_bf16_f32 v5, v5, v2
	v_add_f32_e32 v4, v26, v4
	ds_write_b16 v30, v5 offset:23040
	v_mul_f32_e32 v5, 0xbfb8aa3b, v4
	v_exp_f32_e32 v5, v5
	v_mul_f32_e32 v23, 0x3fb8aa3b, v4
	v_exp_f32_e32 v23, v23
	v_mul_f32_e32 v22, v38, v22
	v_cvt_pk_bf16_f32 v22, v22, v2
	v_sub_f32_e32 v24, v4, v3
	ds_write_b16 v30, v22 offset:144
	v_mul_f32_e32 v22, v36, v5
	v_mul_f32_e32 v24, 0x3fb8aa3b, v24
	v_cvt_pk_bf16_f32 v22, v22, v2
	v_exp_f32_e32 v24, v24
	ds_write_b16 v30, v22 offset:4752
	v_mul_f32_e32 v22, v27, v23
	v_cvt_pk_bf16_f32 v22, v22, v2
	ds_write_b16 v30, v22 offset:9360
	v_mul_f32_e32 v22, v37, v23
	v_cvt_pk_bf16_f32 v22, v22, v2
	ds_write_b16 v30, v22 offset:13968
	v_mul_f32_e32 v22, v27, v24
	v_cvt_pk_bf16_f32 v22, v22, v2
	ds_write_b16 v30, v22 offset:18576
	v_mul_f32_e32 v22, v37, v24
	v_cvt_pk_bf16_f32 v22, v22, v2
	v_add_f32_e32 v4, v28, v4
	ds_write_b16 v30, v22 offset:23184
	v_mul_f32_e32 v22, 0xbfb8aa3b, v4
	v_exp_f32_e32 v22, v22
	v_mul_f32_e32 v23, 0x3fb8aa3b, v4
	v_exp_f32_e32 v23, v23
	v_mul_f32_e32 v5, v41, v5
	v_cvt_pk_bf16_f32 v5, v5, v2
	v_sub_f32_e32 v4, v4, v3
	ds_write_b16 v30, v5 offset:288
	v_mul_f32_e32 v5, v39, v22
	v_mul_f32_e32 v4, 0x3fb8aa3b, v4
	v_cvt_pk_bf16_f32 v5, v5, v2
	v_exp_f32_e32 v4, v4
	ds_write_b16 v30, v5 offset:4896
	v_mul_f32_e32 v5, v29, v23
	v_cvt_pk_bf16_f32 v5, v5, v2
	ds_write_b16 v30, v5 offset:9504
	v_mul_f32_e32 v5, v40, v23
	v_cvt_pk_bf16_f32 v5, v5, v2
	ds_write_b16 v30, v5 offset:14112
	v_mul_f32_e32 v5, v29, v4
	v_mul_f32_e32 v4, v40, v4
	v_cvt_pk_bf16_f32 v5, v5, v2
	ds_write_b16 v30, v5 offset:18720
	v_cvt_pk_bf16_f32 v4, v4, v2
	ds_write_b16 v30, v4 offset:23328
	v_cndmask_b32_e64 v4, 0, 1, s[24:25]
	v_cmp_ne_u32_e64 s[30:31], 1, v4
	s_cbranch_vccnz .LBB0_540
	v_mul_f32_e32 v3, 0xbfb8aa3b, v3
	v_exp_f32_e32 v3, v3
	ds_write_b32 v112, v3

.LBB0_3324:
	s_waitcnt lgkmcnt(0)
	s_barrier
	ds_read2st64_b32 v[176:177], v111 offset0:244 offset1:245
	ds_read2st64_b32 v[178:179], v111 offset0:246 offset1:247
	ds_read2st64_b32 v[180:181], v111 offset0:248 offset1:249
	ds_read2st64_b32 v[182:183], v111 offset0:250 offset1:251
	ds_read2st64_b32 v[184:185], v111 offset0:252 offset1:253
	ds_read2st64_b32 v[186:187], v111 offset0:254 offset1:255
	ds_read2st64_b32 v[188:189], v112 offset0:12 offset1:13
	ds_read2st64_b32 v[190:191], v112 offset0:14 offset1:15
	ds_read2st64_b32 v[192:193], v112 offset0:16 offset1:17
	ds_read2st64_b32 v[194:195], v112 offset0:18 offset1:19
	ds_read2st64_b32 v[196:197], v112 offset0:20 offset1:21
	ds_read2st64_b32 v[198:199], v112 offset0:22 offset1:23
	s_andn2_b64 vcc, exec, s[96:97]
	s_waitcnt lgkmcnt(11)
	ds_read2st64_b32 v[200:201], v112 offset0:24 offset1:25
	v_add_f32_e32 v3, 0, v176
	v_add_f32_e32 v3, v3, v177
	s_waitcnt lgkmcnt(11)
	ds_read2st64_b32 v[202:203], v112 offset0:26 offset1:27
	v_add_f32_e32 v3, v3, v178
	v_add_f32_e32 v3, v3, v179
	v_cndmask_b32_e64 v42, 0, v3, s[42:43]
	s_waitcnt lgkmcnt(11)
	ds_read2st64_b32 v[204:205], v112 offset0:28 offset1:29
	v_add_f32_e32 v3, v3, v180
	v_add_f32_e32 v3, v3, v181
	s_waitcnt lgkmcnt(11)
	ds_read2st64_b32 v[206:207], v112 offset0:30 offset1:31
	v_add_f32_e32 v3, v3, v182
	v_add_f32_e32 v3, v3, v183
	v_cndmask_b32_e64 v42, v42, v3, s[68:69]
	s_waitcnt lgkmcnt(11)
	v_add_f32_e32 v3, v3, v184
	v_add_f32_e32 v3, v3, v185
	s_waitcnt lgkmcnt(10)
	v_add_f32_e32 v3, v3, v186
	v_add_f32_e32 v3, v3, v187
	v_cndmask_b32_e64 v42, v42, v3, s[10:11]
	s_waitcnt lgkmcnt(9)
	v_add_f32_e32 v3, v3, v188
	v_add_f32_e32 v3, v3, v189
	s_waitcnt lgkmcnt(8)
	v_add_f32_e32 v3, v3, v190
	v_add_f32_e32 v3, v3, v191
	v_cndmask_b32_e64 v42, v42, v3, s[12:13]
	s_waitcnt lgkmcnt(7)
	v_add_f32_e32 v3, v3, v192
	v_add_f32_e32 v3, v3, v193
	s_waitcnt lgkmcnt(6)
	v_add_f32_e32 v3, v3, v194
	v_add_f32_e32 v3, v3, v195
	v_cndmask_b32_e64 v42, v42, v3, s[14:15]
	s_waitcnt lgkmcnt(5)
	v_add_f32_e32 v3, v3, v196
	v_add_f32_e32 v3, v3, v197
	s_waitcnt lgkmcnt(4)
	v_add_f32_e32 v3, v3, v198
	v_add_f32_e32 v3, v3, v199
	v_cndmask_b32_e64 v42, v42, v3, s[16:17]
	s_waitcnt lgkmcnt(3)
	v_add_f32_e32 v3, v3, v200
	v_add_f32_e32 v3, v3, v201
	s_waitcnt lgkmcnt(2)
	v_add_f32_e32 v3, v3, v202
	v_add_f32_e32 v3, v3, v203
	v_cndmask_b32_e64 v42, v42, v3, s[18:19]
	s_waitcnt lgkmcnt(1)
	v_add_f32_e32 v3, v3, v204
	v_add_f32_e32 v3, v3, v205
	s_waitcnt lgkmcnt(0)
	v_add_f32_e32 v3, v3, v206
	v_add_f32_e32 v4, v22, v42
	v_mul_f32_e32 v22, 0xbfb8aa3b, v42
	v_exp_f32_e32 v22, v22
	v_add_f32_e32 v3, v3, v207
	v_mul_f32_e32 v5, 0xbfb8aa3b, v4
	v_exp_f32_e32 v5, v5
	v_mul_f32_e32 v42, 0x3fb8aa3b, v4
	v_exp_f32_e32 v42, v42
	v_mul_f32_e32 v22, v31, v22
	v_cvt_pk_bf16_f32 v22, v22, v2
	v_add_u32_e32 v31, s90, v113
	v_sub_f32_e32 v43, v4, v3
	ds_write_b16 v31, v22
	v_mul_f32_e32 v22, v32, v5
	v_mul_f32_e32 v43, 0x3fb8aa3b, v43
	v_cvt_pk_bf16_f32 v22, v22, v2
	v_exp_f32_e32 v43, v43
	ds_write_b16 v31, v22 offset:4608
	v_mul_f32_e32 v22, v23, v42
	v_cvt_pk_bf16_f32 v22, v22, v2
	ds_write_b16 v31, v22 offset:9216
	v_mul_f32_e32 v22, v30, v42
	v_cvt_pk_bf16_f32 v22, v22, v2
	ds_write_b16 v31, v22 offset:13824
	v_mul_f32_e32 v22, v23, v43
	v_cvt_pk_bf16_f32 v22, v22, v2
	ds_write_b16 v31, v22 offset:18432
	v_mul_f32_e32 v22, v30, v43
	v_cvt_pk_bf16_f32 v22, v22, v2
	v_add_f32_e32 v4, v24, v4
	ds_write_b16 v31, v22 offset:23040
	v_mul_f32_e32 v22, 0xbfb8aa3b, v4
	v_exp_f32_e32 v22, v22
	v_mul_f32_e32 v23, 0x3fb8aa3b, v4
	v_exp_f32_e32 v23, v23
	v_mul_f32_e32 v5, v34, v5
	v_cvt_pk_bf16_f32 v5, v5, v2
	v_add_u32_e32 v30, s91, v113
	v_sub_f32_e32 v24, v4, v3
	ds_write_b16 v30, v5
	v_mul_f32_e32 v5, v35, v22
	v_mul_f32_e32 v24, 0x3fb8aa3b, v24
	v_cvt_pk_bf16_f32 v5, v5, v2
	v_exp_f32_e32 v24, v24
	ds_write_b16 v30, v5 offset:4608
	v_mul_f32_e32 v5, v25, v23
	v_cvt_pk_bf16_f32 v5, v5, v2
	ds_write_b16 v30, v5 offset:9216
	v_mul_f32_e32 v5, v33, v23
	v_cvt_pk_bf16_f32 v5, v5, v2
	ds_write_b16 v30, v5 offset:13824
	v_mul_f32_e32 v5, v25, v24
	v_cvt_pk_bf16_f32 v5, v5, v2
	ds_write_b16 v30, v5 offset:18432
	v_mul_f32_e32 v5, v33, v24
	v_cvt_pk_bf16_f32 v5, v5, v2
	v_add_f32_e32 v4, v26, v4
	ds_write_b16 v30, v5 offset:23040
	v_mul_f32_e32 v5, 0xbfb8aa3b, v4
	v_exp_f32_e32 v5, v5
	v_mul_f32_e32 v23, 0x3fb8aa3b, v4
	v_exp_f32_e32 v23, v23
	v_mul_f32_e32 v22, v37, v22
	v_cvt_pk_bf16_f32 v22, v22, v2
	v_sub_f32_e32 v24, v4, v3
	ds_write_b16 v30, v22 offset:144
	v_mul_f32_e32 v22, v38, v5
	v_mul_f32_e32 v24, 0x3fb8aa3b, v24
	v_cvt_pk_bf16_f32 v22, v22, v2
	v_exp_f32_e32 v24, v24
	ds_write_b16 v30, v22 offset:4752
	v_mul_f32_e32 v22, v27, v23
	v_cvt_pk_bf16_f32 v22, v22, v2
	ds_write_b16 v30, v22 offset:9360
	v_mul_f32_e32 v22, v36, v23
	v_cvt_pk_bf16_f32 v22, v22, v2
	ds_write_b16 v30, v22 offset:13968
	v_mul_f32_e32 v22, v27, v24
	v_cvt_pk_bf16_f32 v22, v22, v2
	ds_write_b16 v30, v22 offset:18576
	v_mul_f32_e32 v22, v36, v24
	v_cvt_pk_bf16_f32 v22, v22, v2
	v_add_f32_e32 v4, v28, v4
	ds_write_b16 v30, v22 offset:23184
	v_mul_f32_e32 v22, 0xbfb8aa3b, v4
	v_exp_f32_e32 v22, v22
	v_mul_f32_e32 v23, 0x3fb8aa3b, v4
	v_exp_f32_e32 v23, v23
	v_mul_f32_e32 v5, v40, v5
	v_cvt_pk_bf16_f32 v5, v5, v2
	v_sub_f32_e32 v4, v4, v3
	ds_write_b16 v30, v5 offset:288
	v_mul_f32_e32 v5, v41, v22
	v_mul_f32_e32 v4, 0x3fb8aa3b, v4
	v_cvt_pk_bf16_f32 v5, v5, v2
	v_exp_f32_e32 v4, v4
	ds_write_b16 v30, v5 offset:4896
	v_mul_f32_e32 v5, v29, v23
	v_cvt_pk_bf16_f32 v5, v5, v2
	ds_write_b16 v30, v5 offset:9504
	v_mul_f32_e32 v5, v39, v23
	v_cvt_pk_bf16_f32 v5, v5, v2
	ds_write_b16 v30, v5 offset:14112
	v_mul_f32_e32 v5, v29, v4
	v_mul_f32_e32 v4, v39, v4
	v_cvt_pk_bf16_f32 v5, v5, v2
	ds_write_b16 v30, v5 offset:18720
	v_cvt_pk_bf16_f32 v4, v4, v2
	ds_write_b16 v30, v4 offset:23328
	v_cndmask_b32_e64 v4, 0, 1, s[96:97]
	v_cmp_ne_u32_e64 s[30:31], 1, v4
	s_cbranch_vccnz .LBB0_3326
	v_mul_f32_e32 v3, 0xbfb8aa3b, v3
	v_exp_f32_e32 v3, v3
	ds_write_b32 v114, v3

.LBB0_3717:
	s_or_b64 exec, exec, s[0:1]
	v_readlane_b32 s0, v253, 52
	v_readlane_b32 s1, v253, 53
	s_waitcnt lgkmcnt(0)
	s_barrier
	v_mov_b32_e32 v10, v0
	s_and_b64 vcc, exec, s[0:1]
	v_readfirstlane_b32 s26, v10
	s_cbranch_vccz .Lfd3_2814
	s_and_b32 s0, s96, 0x7fffff00
	s_mov_b64 s[2:3], 0
	s_cmpk_eq_i32 s0, 0x200
	s_mov_b64 s[0:1], 0
	s_cbranch_scc0 .Lfd3_2811
	s_bfe_u32 s0, s96, 0x20004
	s_or_b32 s16, s0, 0x80
	s_lshl_b32 s0, s96, 8
	s_bfe_u32 s18, s96, 0x20006
	s_and_b32 s40, s0, 0xf00
	s_mov_b64 s[0:1], -1

.Lfd3_2819:
	v_ashrrev_i32_e32 v3, 31, v10
	v_lshrrev_b32_e32 v3, 26, v3
	v_add_u32_e32 v3, v10, v3
	v_ashrrev_i32_e32 v11, 6, v3
	v_bfe_i32 v3, v10, 27, 1
	v_lshlrev_b32_e32 v2, 4, v10
	v_lshrrev_b32_e32 v3, 22, v3
	v_add_u32_e32 v3, v2, v3
	v_and_b32_e32 v3, 0xfffffc00, v3
	v_sub_u32_e32 v3, v2, v3
	v_lshrrev_b32_e32 v4, 4, v3
	v_bitop3_b32 v4, v4, v3, 32 bitop3:0x6c
	v_ashrrev_i32_e32 v3, 31, v3
	v_lshrrev_b32_e32 v3, 26, v3
	v_add_u32_e32 v3, v4, v3
	v_ashrrev_i32_e32 v12, 6, v3
	v_mul_i32_i24_e32 v6, 64, v12
	v_sub_u32_e32 v4, v4, v6
	v_mov_b32_e32 v6, 1
	v_lshlrev_b32_e32 v5, 3, v11
	v_lshlrev_b32_e32 v3, 5, v11
	v_ashrrev_i16_sdwa v4, v6, sext(v4) dst_sel:DWORD dst_unused:UNUSED_PAD src0_sel:DWORD src1_sel:BYTE_0
	v_and_b32_e32 v5, 0x7fff0, v5
	v_and_b32_e32 v3, 32, v3
	v_bfe_i32 v13, v4, 0, 16
	v_add_u32_e32 v3, v3, v13
	v_add_lshl_u32 v4, v12, v5, 13
	v_add_u32_e32 v2, 0x2000, v2
	v_lshl_add_u32 v130, v3, 1, v4
	v_ashrrev_i32_e32 v3, 31, v2
	v_lshrrev_b32_e32 v3, 22, v3
	v_add_u32_e32 v3, v2, v3
	v_readlane_b32 s44, v252, 36
	v_ashrrev_i32_e32 v14, 10, v3
	v_readlane_b32 s50, v252, 42
	v_mul_i32_i24_e32 v3, 0x400, v14
	v_readlane_b32 s51, v252, 43
	s_add_u32 s27, s50, 0x1800000
	v_sub_u32_e32 v2, v2, v3
	s_addc_u32 s28, s51, 0
	v_lshrrev_b32_e32 v3, 4, v2
	s_ashr_i32 s2, s26, 6
	s_ashr_i32 s17, s16, 31
	s_ashr_i32 s19, s18, 31
	s_ashr_i32 s0, s26, 8
	v_bitop3_b32 v2, v3, v2, 32 bitop3:0x6c
	s_lshl_b32 s29, s2, 10
	s_lshl_b64 s[4:5], s[16:17], 21
	s_lshl_b32 s1, s40, 1
	s_lshl_b64 s[6:7], s[18:19], 21
	v_ashrrev_i32_e32 v4, 31, v2
	s_add_u32 s3, s27, s6
	v_lshrrev_b32_e32 v4, 26, v4
	s_addc_u32 s6, s28, s7
	v_add_u32_e32 v4, v2, v4
	s_add_u32 s22, s3, s1
	v_ashrrev_i32_e32 v15, 6, v4
	v_and_b32_e32 v4, 0xc0, v4
	s_addc_u32 s23, s6, 0
	s_add_i32 s17, s29, 0
	v_sub_u32_e32 v2, v2, v4
	s_add_i32 m0, s17, 0x10000
	v_readlane_b32 s46, v252, 38
	v_lshlrev_b32_e32 v3, 3, v14
	v_lshlrev_b32_e32 v5, 5, v14
	v_ashrrev_i16_sdwa v2, v6, sext(v2) dst_sel:DWORD dst_unused:UNUSED_PAD src0_sel:DWORD src1_sel:BYTE_0
	global_load_lds_dwordx4 v130, s[22:23]
	s_add_i32 m0, s17, 0x12000
	v_readlane_b32 s47, v252, 39
	v_and_b32_e32 v3, 0x7fff0, v3
	v_and_b32_e32 v5, 32, v5
	v_bfe_i32 v16, v2, 0, 16
	s_add_u32 s3, s46, s4
	v_add_u32_e32 v2, v5, v16
	v_add_lshl_u32 v3, v15, v3, 13
	s_addc_u32 s4, s47, s5
	v_lshl_add_u32 v132, v2, 1, v3
	s_add_u32 s20, s3, s1
	global_load_lds_dwordx4 v132, s[22:23]
	s_addc_u32 s21, s4, 0
	s_mov_b32 m0, s17
	s_add_i32 s19, s17, 0x2000
	global_load_lds_dwordx4 v130, s[20:21]
	s_mov_b32 m0, s19
	s_add_u32 s4, s22, 0x100000
	global_load_lds_dwordx4 v132, s[20:21]
	s_addc_u32 s5, s23, 0
	s_add_i32 m0, s17, 0x14000
	v_mov_b32_e32 v131, 0
	global_load_lds_dwordx4 v130, s[4:5]
	s_add_i32 m0, s17, 0x16000
	v_mov_b32_e32 v133, v131
	global_load_lds_dwordx4 v132, s[4:5]
	s_add_u32 s4, s20, 0x100000
	s_addc_u32 s5, s21, 0
	s_add_i32 s30, s17, 0x4000
	s_mov_b32 m0, s30
	s_add_i32 s31, s17, 0x6000
	global_load_lds_dwordx4 v130, s[4:5]
	s_mov_b32 m0, s31
	s_mov_b32 s1, 0
	global_load_lds_dwordx4 v132, s[4:5]
	v_lshl_add_u64 v[8:9], s[22:23], 0, v[130:131]
	v_lshl_add_u64 v[6:7], s[22:23], 0, v[132:133]
	v_lshl_add_u64 v[4:5], s[20:21], 0, v[130:131]
	s_cmp_lg_u32 s0, 1
	v_lshl_add_u64 v[2:3], s[20:21], 0, v[132:133]
	v_readlane_b32 s45, v252, 37
	v_readlane_b32 s48, v252, 40
	v_readlane_b32 s49, v252, 41
	v_readlane_b32 s52, v252, 44
	v_readlane_b32 s53, v252, 45
	v_readlane_b32 s54, v252, 46
	v_readlane_b32 s55, v252, 47
	v_readlane_b32 s56, v252, 48
	v_readlane_b32 s57, v252, 49
	v_readlane_b32 s58, v252, 50
	v_readlane_b32 s59, v252, 51
	s_cbranch_scc1 .Lfd3_2821
	s_barrier

.Lfd3_2841:
	s_waitcnt vmcnt(0)
	s_waitcnt vmcnt(0) lgkmcnt(0)
	s_barrier
	s_and_saveexec_b64 s[0:1], s[94:95]
	s_cbranch_execz .LBB0_3798
	s_add_i32 s2, 0, 0x27fc0
	v_mov_b32_e32 v0, s2
	s_waitcnt vmcnt(0) expcnt(0) lgkmcnt(0)
	ds_read_b32 v2, v0
	s_add_i32 s2, 0, 0x27fc4
	v_mov_b32_e32 v0, s2
	ds_read_b32 v0, v0
	s_waitcnt lgkmcnt(1)
	v_cmp_ne_u32_e32 vcc, 0, v2
	s_cbranch_vccnz .LBB0_3762
	v_readlane_b32 s2, v252, 55
	v_readlane_b32 s3, v252, 56
	v_readlane_b32 s8, v252, 0
	s_load_dwordx2 s[6:7], s[2:3], 0x4
	v_readlane_b32 s10, v252, 2
	v_readlane_b32 s11, v252, 3
	s_add_u32 s2, s10, 0x1000
	s_addc_u32 s3, s11, 0
	v_readlane_b32 s9, v252, 1
	s_add_u32 s4, s10, 0x1100
	s_addc_u32 s5, s11, 0
	v_readlane_b32 s8, v253, 28
	s_waitcnt lgkmcnt(0)
	s_mul_i32 s16, s6, s8
	s_add_u32 s6, s10, 0x1200
	s_mul_i32 s16, s16, s7
	s_addc_u32 s7, s11, 0
	v_readlane_b32 s9, v253, 29
	s_add_u32 s8, s10, 0x1300
	s_addc_u32 s9, s11, 0
	s_mov_b32 s17, 1
	v_mov_b32_e32 v16, 0
	s_branch .LBB0_3750

.LBB0_3798:
	s_or_b64 exec, exec, s[0:1]
	s_waitcnt lgkmcnt(0)
	s_barrier
	v_cndmask_b32_e64 v0, v0, 0, s[94:95]
	v_readlane_b32 s60, v253, 30
	v_mov_b32_e32 v2, v0
	v_readlane_b32 s0, v252, 57
	v_lshrrev_b32_e32 v2, 6, v2
	s_nop 0
	v_add_u32_e32 v14, s0, v2
	s_movk_i32 s0, 0x400
	v_mov_b32_e32 v2, v0
	v_cmp_gt_i32_e32 vcc, s0, v14
	s_and_saveexec_b64 s[0:1], vcc
	s_cbranch_execz .Lfo3_2896
	v_add_u32_e32 v4, 0x8000, v14
	v_ashrrev_i32_e32 v5, 31, v4
	v_lshlrev_b32_e32 v3, 4, v2
	v_readlane_b32 s4, v252, 36
	v_lshlrev_b32_e32 v15, 8, v4
	v_readlane_b32 s2, v253, 28
	v_lshlrev_b64 v[4:5], 12, v[4:5]
	v_and_b32_e32 v2, 63, v2
	v_and_b32_e32 v6, 0x3f0, v3
	v_mov_b32_e32 v7, 0
	v_readlane_b32 s5, v252, 37
	v_readlane_b32 s6, v252, 38
	v_readlane_b32 s7, v252, 39
	v_readlane_b32 s8, v252, 40
	v_readlane_b32 s9, v252, 41
	v_readlane_b32 s10, v252, 42
	v_readlane_b32 s11, v252, 43
	v_readlane_b32 s12, v252, 44
	v_readlane_b32 s13, v252, 45
	v_readlane_b32 s14, v252, 46
	v_readlane_b32 s15, v252, 47
	v_readlane_b32 s16, v252, 48
	v_readlane_b32 s17, v252, 49
	v_readlane_b32 s18, v252, 50
	v_readlane_b32 s19, v252, 51
	v_readlane_b32 s3, v253, 29
	v_lshl_or_b32 v4, v2, 4, v4
	s_ashr_i32 s61, s60, 31
	v_lshl_add_u64 v[8:9], s[12:13], 0, v[6:7]
	s_lshl_b32 s6, s2, 11
	v_lshl_add_u64 v[10:11], s[88:89], 0, v[4:5]
	s_lshl_b64 s[2:3], s[60:61], 12
	s_mov_b64 s[4:5], 0
	s_mov_b32 s7, 0x23c0000
	s_mov_b32 s8, 0x3000000
	s_mov_b32 s9, 0x3040000
	s_mov_b32 s10, 0x3080000
	s_mov_b32 s11, 0x30c0000
	s_mov_b32 s12, 0x3100000
	s_mov_b32 s13, 0x3140000
	s_mov_b32 s14, 0x3180000
	s_mov_b32 s15, 0x31c0000
	s_mov_b32 s16, 0x3200000
	s_mov_b32 s17, 0x3240000
	s_mov_b32 s18, 0x3280000
	s_mov_b32 s19, 0x32c0000
	s_mov_b32 s20, 0x3300000
	s_mov_b32 s21, 0x3340000
	s_mov_b32 s22, 0x3380000
	s_mov_b32 s23, 0x33c0000
	s_mov_b32 s24, 0x83ff

.Lfo3_2896:
	s_or_b64 exec, exec, s[0:1]
	s_endpgm
